# combined: SQRELU+out-proj RESID epilogues restructured, scan prefetch wait moved to its consumer, staggered start of the short half in 4.5-round RESID GEMMs
# speedup vs baseline: 1.0047x; 1.0047x over previous
; #define PROLOGUE_STAGES(br_, bc_) do { \
;     STAGEB(SB(0, 0), bc_, 0); STAGEA(SA(0, 0), br_, 0); STAGEB(SB(0, 1), (bc_) + HALF, 0); STAGEA(SA(0, 1), (br_) + HALF, 0); \
;     STAGEB(SB(1, 0), bc_, 1); STAGEA(SA(1, 0), br_, 1); STAGEB(SB(1, 1), (bc_) + HALF, 1); } while (0)
; template <int EPI>
; DI void gemm_phase(const u16* __restrict__ A, int lda, const u16* __restrict__ Bt, int ldb,
;                    int M, int N, int K, const Epi& e, unsigned char* shmraw, int wv, int slot) {
;     ...
;   int T = slot, pm = 0, pn = 0, st_;
;   while ((st_ = gemm_decode(T, nsuper, nNs, SWM, SWN, nM, pm, pn)) == 0) T += nb;
;   if (st_ < 0) return;
;     ...
;   PROLOGUE_STAGES(pm * BM, pn * BM);
.LBB0_674:
	s_lshl_b32 vcc_lo, s28, 5
	s_add_i32 vcc_hi, s34, -1
	s_and_b32 vcc_lo, vcc_lo, vcc_hi
	s_cmp_eq_u32 vcc_lo, 0
	s_cbranch_scc1 .Lmy_stg_r642
	s_sub_i32 vcc_hi, s29, s34
	s_cmp_lt_i32 vcc_hi, vcc_lo
	s_cbranch_scc1 .Lmy_stg_r642
	s_sleep 127
	s_sleep 127
	s_sleep 127

; DI void phase_scan(const Params& p, int j, unsigned char* shm, int wv) {
;     ...
;     {
;       const float are = p.in[12][dg * 64 + pst], aim = p.in[13][dg * 64 + pst];
;       const float dt = expf(p.in[14][dg]);
;       const float er = expf(are * dt), ang = aim * dt;
;       abr = er * cosf(ang); abi = er * sinf(ang);
;       const float nr = abr - 1.f, ni = abi, den = are * are + aim * aim;
;       const float cr = (nr * are + ni * aim) / den, ci = (ni * are - nr * aim) / den;
;       const float* bre = p.in[15] + ((size_t)dg * 64 + pst) * 16;
;       const float* bim = p.in[16] + ((size_t)dg * 64 + pst) * 16;
;       __builtin_amdgcn_wave_barrier();
; #pragma unroll
;       for (int h = 0; h < 16; h += 2) {
;         float br0 = bre[h], bi0 = bim[h], br1 = bre[h + 1], bi1 = bim[h + 1];
;         *(unsigned*)(BbT + (2 * pst) * 16 + h) = pack2(cr * br0 - ci * bi0, cr * br1 - ci * bi1);
;         *(unsigned*)(BbT + (2 * pst + 1) * 16 + h) = pack2(cr * bi0 + ci * br0, cr * bi1 + ci * br1);
;       }
.LBB0_853:
	s_or_b64 exec, exec, s[8:9]
	s_waitcnt vmcnt(0)
	v_mul_f32_e32 v9, v4, v9
	v_mul_f32_e32 v12, 0x3fb8aa3b, v9
	s_mov_b32 s0, 0x3fb8aa3b
	v_fma_f32 v13, v9, s0, -v12
	v_rndne_f32_e32 v14, v12
	v_fmac_f32_e32 v13, 0x32a5705f, v9
	v_sub_f32_e32 v12, v12, v14
	v_add_f32_e32 v12, v12, v13
	v_cvt_i32_f32_e32 v13, v14
	v_exp_f32_e32 v12, v12
	s_mov_b32 s0, 0xc2ce8ed0
	v_cmp_ngt_f32_e32 vcc, s0, v9
	s_mov_b32 s0, 0x42b17218
	v_ldexp_f32 v12, v12, v13
	v_cndmask_b32_e32 v12, 0, v12, vcc
	v_cmp_nlt_f32_e32 vcc, s0, v9
	v_mov_b32_e32 v9, 0x7f800000
	v_lshlrev_b64 v[16:17], 10, v[0:1]
	v_cndmask_b32_e32 v95, v9, v12, vcc
	v_mul_f32_e32 v9, v8, v8
	v_or_b32_e32 v12, v16, v58
	v_mov_b32_e32 v13, v17
	v_readlane_b32 s0, v251, 8
	v_mov_b32_e32 v19, 0x3c0881c4
	v_lshlrev_b64 v[12:13], 2, v[12:13]
	v_readlane_b32 s1, v251, 9
	v_readlane_b32 s2, v251, 10
	v_readlane_b32 s3, v251, 11
	v_readlane_b32 s4, v251, 12
	v_readlane_b32 s5, v251, 13
	v_readlane_b32 s6, v251, 14
	v_readlane_b32 s7, v251, 15
	v_readlane_b32 s8, v251, 16
	v_readlane_b32 s9, v251, 17
	v_readlane_b32 s10, v251, 18
	v_readlane_b32 s11, v251, 19
	v_readlane_b32 s12, v251, 20
	v_readlane_b32 s13, v251, 21
	v_readlane_b32 s14, v251, 22
	v_readlane_b32 s15, v251, 23
	v_fmamk_f32 v0, v9, 0xb94c1982, v19
	v_fmaak_f32 v0, v9, v0, 0xbe2aaa9d
	v_lshl_add_u64 v[36:37], s[14:15], 0, v[12:13]
	v_readlane_b32 s0, v251, 42
	v_readlane_b32 s1, v251, 43
	v_mul_f32_e32 v0, v9, v0
	v_mov_b32_e32 v32, 0xbab64f3b
	v_lshl_add_u64 v[38:39], s[0:1], 0, v[12:13]
	v_fmac_f32_e32 v8, v8, v0
	v_fmamk_f32 v0, v9, 0x37d75334, v32
	global_load_dwordx4 v[12:15], v[38:39], off offset:16
	global_load_dwordx4 v[20:23], v[38:39], off
	global_load_dwordx4 v[24:27], v[36:37], off offset:16
	global_load_dwordx4 v[28:31], v[36:37], off
	v_fmaak_f32 v0, v9, v0, 0x3d2aabf7
	v_readlane_b32 s2, v251, 44
	v_readlane_b32 s3, v251, 45
	v_readlane_b32 s4, v251, 46
	v_readlane_b32 s5, v251, 47
	v_readlane_b32 s6, v251, 48
	v_readlane_b32 s7, v251, 49
	v_readlane_b32 s8, v251, 50
	v_readlane_b32 s9, v251, 51
	v_readlane_b32 s10, v251, 52
	v_readlane_b32 s11, v251, 53
	v_readlane_b32 s12, v251, 54
	v_readlane_b32 s13, v251, 55
	v_readlane_b32 s14, v251, 56
	v_readlane_b32 s15, v251, 57
	v_fmaak_f32 v0, v9, v0, 0xbf000004
	v_fma_f32 v0, v9, v0, 1.0
	v_and_b32_e32 v9, 1, v7
	v_readlane_b32 s0, v255, 2
	v_cmp_eq_u32_e32 vcc, 0, v9
	v_readlane_b32 s1, v255, 3
	v_lshlrev_b32_e32 v7, 30, v7
	v_cndmask_b32_e64 v0, -v8, v0, vcc
	s_movk_i32 s1, 0x1f8
	v_bitop3_b32 v0, v7, v0, s0 bitop3:0x6c
	v_cmp_class_f32_e64 vcc, v5, s1
	v_mov_b32_e32 v8, 0x7fc00000
	v_readlane_b32 s8, v255, 10
	v_cndmask_b32_e32 v96, v8, v0, vcc
	v_mul_f32_e32 v0, v11, v11
	v_fmamk_f32 v7, v0, 0xb94c1982, v19
	v_fmaak_f32 v7, v0, v7, 0xbe2aaa9d
	v_mul_f32_e32 v7, v0, v7
	v_fmac_f32_e32 v11, v11, v7
	v_fmamk_f32 v7, v0, 0x37d75334, v32
	global_load_dwordx4 v[32:35], v[38:39], off offset:48
	global_load_dwordx4 v[40:43], v[38:39], off offset:32
	global_load_dwordx4 v[44:47], v[36:37], off offset:48
	global_load_dwordx4 v[48:51], v[36:37], off offset:32
	v_fmaak_f32 v7, v0, v7, 0x3d2aabf7
	v_fmaak_f32 v7, v0, v7, 0xbf000004
	v_readlane_b32 s9, v255, 11
	v_fma_f32 v0, v0, v7, 1.0
	v_and_b32_e32 v7, 1, v10
	v_cmp_eq_u32_e64 s[8:9], 0, v7
	v_lshlrev_b32_e32 v7, 30, v10
	v_and_b32_e32 v7, 0x80000000, v7
	v_xor_b32_e32 v5, v6, v5
	v_cndmask_b32_e64 v0, v0, v11, s[8:9]
	v_xor_b32_e32 v5, v5, v7
	v_xor_b32_e32 v0, v5, v0
	v_cndmask_b32_e32 v0, v8, v0, vcc
	v_mul_f32_e32 v38, v95, v0
	v_mov_b32_e32 v39, v2
	v_fma_f32 v6, v95, v96, -1.0
	v_mov_b32_e32 v7, v4
	v_pk_mul_f32 v[8:9], v[2:3], v[38:39] op_sel_hi:[0,1]
	v_pk_fma_f32 v[8:9], v[4:5], v[6:7], v[8:9] op_sel_hi:[0,1,1]
	v_div_scale_f32 v0, s[8:9], v9, v9, v8
	v_rcp_f32_e32 v7, v0
	v_mov_b32_e32 v39, v6
	v_or_b32_e32 v16, v16, v62
	v_ashrrev_i32_e32 v36, 6, v3
	v_fma_f32 v5, -v0, v7, 1.0
	v_fmac_f32_e32 v7, v5, v7
	v_div_scale_f32 v5, vcc, v8, v9, v8
	v_mul_f32_e32 v10, v5, v7
	v_fma_f32 v11, -v0, v10, v5
	v_fmac_f32_e32 v10, v11, v7
	v_fma_f32 v0, -v0, v10, v5
	v_mov_b32_e32 v5, v2
	v_pk_mul_f32 v[4:5], v[4:5], v[38:39]
	v_div_fmas_f32 v0, v0, v7, v10
	v_sub_f32_e32 v2, v4, v5
	v_div_scale_f32 v4, s[8:9], v9, v9, v2
	v_rcp_f32_e32 v5, v4
	v_div_fixup_f32 v0, v0, v9, v8
	s_waitcnt vmcnt(7)
	v_pk_mul_f32 v[10:11], v[0:1], v[12:13] op_sel_hi:[0,1]
	v_lshlrev_b32_e32 v37, 8, v36
	v_fma_f32 v6, -v4, v5, 1.0
	v_fmac_f32_e32 v5, v6, v5
	v_div_scale_f32 v6, vcc, v2, v9, v2
	v_mul_f32_e32 v7, v6, v5
	v_fma_f32 v8, -v4, v7, v6
	v_fmac_f32_e32 v7, v8, v5
	v_fma_f32 v4, -v4, v7, v6
	v_div_fmas_f32 v4, v4, v5, v7
	v_div_fixup_f32 v2, v4, v9, v2
	s_waitcnt vmcnt(6)
	v_pk_mul_f32 v[6:7], v[20:21], v[0:1] op_sel_hi:[1,0]
	v_pk_mul_f32 v[4:5], v[20:21], v[2:3] op_sel_hi:[1,0]
	s_waitcnt vmcnt(4)
	v_pk_fma_f32 v[6:7], v[28:29], v[2:3], v[6:7] op_sel_hi:[1,0,1]
	v_pk_fma_f32 v[4:5], v[28:29], v[0:1], v[4:5] op_sel_hi:[1,0,1] neg_lo:[0,0,1] neg_hi:[0,0,1]
	v_cvt_pk_bf16_f32 v8, v6, v7
	v_pk_mul_f32 v[6:7], v[22:23], v[2:3] op_sel_hi:[1,0]
	v_cvt_pk_bf16_f32 v4, v4, v5
	v_pk_fma_f32 v[6:7], v[30:31], v[0:1], v[6:7] op_sel_hi:[1,0,1] neg_lo:[0,0,1] neg_hi:[0,0,1]
	v_pk_fma_f32 v[10:11], v[2:3], v[24:25], v[10:11] op_sel_hi:[0,1,1]
	v_cvt_pk_bf16_f32 v5, v6, v7
	v_pk_mul_f32 v[6:7], v[22:23], v[0:1] op_sel_hi:[1,0]
	v_cvt_pk_bf16_f32 v10, v10, v11
	v_pk_fma_f32 v[6:7], v[30:31], v[2:3], v[6:7] op_sel_hi:[1,0,1]
	v_mov_b32_e32 v73, v1
	v_cvt_pk_bf16_f32 v9, v6, v7
	v_pk_mul_f32 v[6:7], v[2:3], v[12:13] op_sel_hi:[0,1]
	v_pk_mul_f32 v[12:13], v[2:3], v[14:15] op_sel_hi:[0,1]
	v_pk_fma_f32 v[6:7], v[0:1], v[24:25], v[6:7] op_sel_hi:[0,1,1] neg_lo:[0,0,1] neg_hi:[0,0,1]
	v_pk_fma_f32 v[12:13], v[0:1], v[26:27], v[12:13] op_sel_hi:[0,1,1] neg_lo:[0,0,1] neg_hi:[0,0,1]
	v_cvt_pk_bf16_f32 v6, v6, v7
	v_cvt_pk_bf16_f32 v7, v12, v13
	ds_write_b128 v90, v[4:7]
	v_pk_mul_f32 v[4:5], v[0:1], v[14:15] op_sel_hi:[0,1]
	v_pk_fma_f32 v[4:5], v[2:3], v[26:27], v[4:5] op_sel_hi:[0,1,1]
	s_waitcnt vmcnt(2)
; DI void phase_scan(const Params& p, int j, unsigned char* shm, int wv) {
;     ...
;     s16x4 bop[8];
; #pragma unroll
;     for (int nb = 0; nb < 8; ++nb) bop[nb] = *(const s16x4*)(BbT + (nb * 16 + col) * 16 + quad * 4);
;     bf16x8 cop[4];
;     {
;       const float* cre = p.in[17] + ((size_t)dg * 16 + col) * 64;
;       const float* cim = p.in[18] + ((size_t)dg * 16 + col) * 64;
; #pragma unroll
;       for (int kb = 0; kb < 4; ++kb) {
;         float4 a = *(const float4*)(cre + kb * 16 + quad * 4), c = *(const float4*)(cim + kb * 16 + quad * 4);
;         uint4 u = make_uint4(pack2(a.x, -c.x), pack2(a.y, -c.y), pack2(a.z, -c.z), pack2(a.w, -c.w));
;         cop[kb] = __builtin_bit_cast(bf16x8, u);
;       }
;     }
;     __builtin_amdgcn_wave_barrier();
;     u16* Rd = (u16*)(p.ws + (d ? R_R1 : R_R0));
;     float hr = 0.f, hi = 0.f;
;     s16x4 ua = *(const s16x4*)(ZS + (size_t)ssm_tok(d, b, col) * 512 + g * 16 + quad * 4);
;     s16x4 ub = *(const s16x4*)(ZS + (size_t)ssm_tok(d, b, 16 + col) * 512 + g * 16 + quad * 4);
;     for (int c = 0; c < 144; ++c) {
;       const int tau0 = c * 16;
;       s16x4 ucur = ua;
;       ua = ub;
;       if (c + 2 < 144) ub = *(const s16x4*)(ZS + (size_t)ssm_tok(d, b, tau0 + 32 + col) * 512 + g * 16 + quad * 4);
	v_pk_mul_f32 v[6:7], v[0:1], v[40:41] op_sel_hi:[0,1]
	v_cvt_pk_bf16_f32 v11, v4, v5
	s_waitcnt vmcnt(0)
	v_pk_fma_f32 v[6:7], v[2:3], v[48:49], v[6:7] op_sel_hi:[0,1,1]
	ds_write_b128 v90, v[8:11] offset:32
	v_pk_mul_f32 v[4:5], v[2:3], v[40:41] op_sel_hi:[0,1]
	v_cvt_pk_bf16_f32 v8, v6, v7
	v_pk_mul_f32 v[6:7], v[2:3], v[42:43] op_sel_hi:[0,1]
	v_pk_fma_f32 v[4:5], v[0:1], v[48:49], v[4:5] op_sel_hi:[0,1,1] neg_lo:[0,0,1] neg_hi:[0,0,1]
	v_pk_fma_f32 v[6:7], v[0:1], v[50:51], v[6:7] op_sel_hi:[0,1,1] neg_lo:[0,0,1] neg_hi:[0,0,1]
	v_cvt_pk_bf16_f32 v4, v4, v5
	v_cvt_pk_bf16_f32 v5, v6, v7
	v_pk_mul_f32 v[6:7], v[0:1], v[42:43] op_sel_hi:[0,1]
	v_pk_fma_f32 v[6:7], v[2:3], v[50:51], v[6:7] op_sel_hi:[0,1,1]
	v_cvt_pk_bf16_f32 v9, v6, v7
	v_pk_mul_f32 v[6:7], v[2:3], v[32:33] op_sel_hi:[0,1]
	v_pk_mul_f32 v[12:13], v[2:3], v[34:35] op_sel_hi:[0,1]
	v_pk_fma_f32 v[6:7], v[0:1], v[44:45], v[6:7] op_sel_hi:[0,1,1] neg_lo:[0,0,1] neg_hi:[0,0,1]
	v_pk_fma_f32 v[12:13], v[0:1], v[46:47], v[12:13] op_sel_hi:[0,1,1] neg_lo:[0,0,1] neg_hi:[0,0,1]
	v_cvt_pk_bf16_f32 v6, v6, v7
	v_cvt_pk_bf16_f32 v7, v12, v13
	v_pk_mul_f32 v[10:11], v[0:1], v[32:33] op_sel_hi:[0,1]
	ds_write_b128 v90, v[4:7] offset:16
	v_pk_mul_f32 v[4:5], v[0:1], v[34:35] op_sel_hi:[0,1]
	v_pk_fma_f32 v[10:11], v[2:3], v[44:45], v[10:11] op_sel_hi:[0,1,1]
	v_pk_fma_f32 v[4:5], v[2:3], v[46:47], v[4:5] op_sel_hi:[0,1,1]
	v_cvt_pk_bf16_f32 v10, v10, v11
	v_cvt_pk_bf16_f32 v11, v4, v5
	v_lshlrev_b64 v[4:5], 2, v[16:17]
	v_lshl_add_u64 v[32:33], v[66:67], 0, v[4:5]
	v_lshl_add_u64 v[34:35], v[68:69], 0, v[4:5]
	v_add_u32_e32 v0, v85, v60
	ds_write_b128 v90, v[8:11] offset:48
	global_load_dwordx4 v[20:23], v[34:35], off
	global_load_dwordx4 v[24:27], v[32:33], off
	global_load_dwordx4 v[28:31], v[34:35], off offset:64
	global_load_dwordx4 v[44:47], v[32:33], off offset:64
	ds_read2st64_b64 v[2:5], v0 offset1:1
	ds_read2st64_b64 v[6:9], v0 offset0:2 offset1:3
	global_load_dwordx4 v[50:53], v[34:35], off offset:128
	global_load_dwordx4 v[54:57], v[32:33], off offset:128
	ds_read2st64_b64 v[10:13], v0 offset0:4 offset1:5
	ds_read2st64_b64 v[14:17], v0 offset0:6 offset1:7
	global_load_dwordx4 v[74:77], v[32:33], off offset:192
	global_load_dwordx4 v[78:81], v[34:35], off offset:192
	v_sub_u32_e32 v34, v37, v82
	v_add_u32_e32 v0, v83, v37
	v_add_u32_e32 v19, 0x100ff, v34
	v_cndmask_b32_e64 v32, v19, v0, s[26:27]
	v_ashrrev_i32_e32 v33, 31, v32
	v_lshlrev_b64 v[32:33], 10, v[32:33]
	v_lshl_add_u64 v[32:33], s[44:45], 0, v[32:33]
	v_lshlrev_b32_e32 v0, 5, v18
	v_lshl_add_u64 v[18:19], v[32:33], 0, v[0:1]
	v_add_u32_e32 v32, v86, v37
	v_add_u32_e32 v33, 0x100ef, v34
	v_cndmask_b32_e64 v32, v33, v32, s[26:27]
	v_ashrrev_i32_e32 v33, 31, v32
	v_lshlrev_b64 v[32:33], 10, v[32:33]
	v_lshl_add_u64 v[32:33], s[44:45], 0, v[32:33]
	v_lshl_add_u64 v[32:33], v[32:33], 0, v[0:1]
	v_lshl_add_u64 v[32:33], v[32:33], 0, v[72:73]
	v_lshl_add_u64 v[18:19], v[18:19], 0, v[72:73]
	global_load_dwordx2 v[40:41], v[32:33], off
	global_load_dwordx2 v[34:35], v[18:19], off
	v_mov_b32_e32 v48, 0
	v_mul_f32_e32 v42, v95, v96
	v_lshlrev_b32_e32 v36, 11, v36
	s_mov_b32 s1, 0
	v_mov_b32_e32 v43, v42
	v_mov_b32_e32 v39, v38
	v_mov_b32_e32 v49, v48
	v_readlane_b32 s2, v255, 4
	v_readlane_b32 s3, v255, 5
	v_readlane_b32 s4, v255, 6
	v_readlane_b32 s5, v255, 7
	v_readlane_b32 s6, v255, 8
	v_readlane_b32 s7, v255, 9
	v_readlane_b32 s10, v255, 12
	v_readlane_b32 s11, v255, 13
	v_readlane_b32 s12, v255, 14
	v_readlane_b32 s13, v255, 15
	v_readlane_b32 s14, v255, 16
	v_readlane_b32 s15, v255, 17
	s_waitcnt vmcnt(9)
	v_xor_b32_e32 v18, 0x80000000, v20
	v_xor_b32_e32 v19, 0x80000000, v21
	v_xor_b32_e32 v20, 0x80000000, v22
	v_xor_b32_e32 v21, 0x80000000, v23
	s_waitcnt vmcnt(8)
	v_cvt_pk_bf16_f32 v18, v24, v18
	v_cvt_pk_bf16_f32 v19, v25, v19
	v_cvt_pk_bf16_f32 v20, v26, v20
	v_cvt_pk_bf16_f32 v21, v27, v21
	s_waitcnt vmcnt(7)
	v_xor_b32_e32 v22, 0x80000000, v28
	v_xor_b32_e32 v23, 0x80000000, v29
	v_xor_b32_e32 v24, 0x80000000, v30
	v_xor_b32_e32 v25, 0x80000000, v31
	s_waitcnt vmcnt(5)
	v_xor_b32_e32 v26, 0x80000000, v50
	v_xor_b32_e32 v27, 0x80000000, v51
	v_xor_b32_e32 v28, 0x80000000, v52
	v_xor_b32_e32 v29, 0x80000000, v53
	s_waitcnt vmcnt(2)
	v_xor_b32_e32 v30, 0x80000000, v78
	v_xor_b32_e32 v31, 0x80000000, v79
	v_xor_b32_e32 v32, 0x80000000, v80
	v_xor_b32_e32 v33, 0x80000000, v81
	v_cvt_pk_bf16_f32 v22, v44, v22
	v_cvt_pk_bf16_f32 v23, v45, v23
	v_cvt_pk_bf16_f32 v24, v46, v24
	v_cvt_pk_bf16_f32 v25, v47, v25
	v_cvt_pk_bf16_f32 v26, v54, v26
	v_cvt_pk_bf16_f32 v27, v55, v27
	v_cvt_pk_bf16_f32 v28, v56, v28
	v_cvt_pk_bf16_f32 v29, v57, v29
	v_cvt_pk_bf16_f32 v30, v74, v30
	v_cvt_pk_bf16_f32 v31, v75, v31
	v_cvt_pk_bf16_f32 v32, v76, v32
	v_cvt_pk_bf16_f32 v33, v77, v33
	v_lshl_add_u64 v[44:45], v[64:65], 0, v[0:1]
	v_lshl_add_u64 v[46:47], v[70:71], 0, v[0:1]
	v_add_u32_e32 v0, 0x8ff, v36
	v_add_u32_e32 v54, 0x100ff, v37
	v_add_u32_e32 v55, 0xffffff00, v36
	v_add_u32_e32 v56, v61, v37
	s_waitcnt vmcnt(1)
	v_mov_b64_e32 v[50:51], v[40:41]
	s_waitcnt vmcnt(0)
	s_branch .LBB0_855
.LBB0_854:
	s_or_b64 exec, exec, s[12:13]
	v_ashrrev_i32_e32 v53, 31, v52
	s_nop 0
	v_cvt_pk_bf16_f32 v34, v34, v35
	v_cvt_pk_bf16_f32 v35, v36, v37
	v_lshlrev_b64 v[36:37], 10, v[52:53]
	v_lshl_add_u64 v[36:37], v[46:47], 0, v[36:37]
	s_add_i32 s1, s1, 1
	global_store_dwordx2 v[36:37], v[34:35], off
	v_add_u32_e32 v56, 16, v56
	s_cmpk_eq_i32 s1, 0x90
	v_mov_b64_e32 v[34:35], v[40:41]
	s_waitcnt vmcnt(1)
	v_mov_b64_e32 v[40:41], v[50:51]
	s_cbranch_scc1 .LBB0_877

; DI void phase_scan(const Params& p, int j, unsigned char* shm, int wv) {
;     ...
; #pragma unroll
;       for (int nb = 0; nb < 8; ++nb) {
;         f32x4 z = {0.f, 0.f, 0.f, 0.f};
;         f32x4 r4 = __builtin_amdgcn_mfma_f32_16x16x16bf16_1k(ucur, bop[nb], z, 0, 0, 0);
; #pragma unroll
;         for (int jj = 0; jj < 4; ++jj) bu[(quad * 4 + jj) * 132 + nb * 16 + col] = r4[jj];
;       }
;       __builtin_amdgcn_wave_barrier();
;       float2 bv[16];
; #pragma unroll
;       for (int t = 0; t < 16; ++t) bv[t] = *(const float2*)(bu + t * 132 + 2 * pst);
; #pragma unroll
;       for (int t = 0; t < 16; ++t) {
;         const float nr = abr * hr - abi * hi + bv[t].x;
;         const float ni = abr * hi + abi * hr + bv[t].y;
;         hr = nr; hi = ni;
;         *(unsigned*)(Hl + t * 136 + 2 * pst) = pack2(hr, hi);
;       }
.LBB0_866:
	s_waitcnt lgkmcnt(3)
	v_mfma_f32_16x16x16_bf16 v[74:77], v[34:35], v[2:3], 0
	v_add_u32_e32 v52, 0x400, v91
	v_add_u32_e32 v57, 0x1800, v92
	s_cmp_gt_u32 s1, 15
	v_mfma_f32_16x16x16_bf16 v[78:81], v[34:35], v[4:5], 0
	s_nop 7
	ds_write2_b32 v91, v74, v78 offset1:16
	ds_write2_b32 v91, v75, v79 offset0:132 offset1:148
	ds_write2_b32 v52, v76, v80 offset0:8 offset1:24
	ds_write2_b32 v52, v77, v81 offset0:140 offset1:156
	s_waitcnt lgkmcnt(6)
	v_mfma_f32_16x16x16_bf16 v[74:77], v[34:35], v[6:7], 0
	s_cselect_b64 s[8:9], -1, 0
	v_mfma_f32_16x16x16_bf16 v[78:81], v[34:35], v[8:9], 0
	s_nop 7
	ds_write2_b32 v91, v74, v78 offset0:32 offset1:48
	ds_write2_b32 v91, v75, v79 offset0:164 offset1:180
	ds_write2_b32 v52, v76, v80 offset0:40 offset1:56
	ds_write2_b32 v52, v77, v81 offset0:172 offset1:188
	s_waitcnt lgkmcnt(9)
	v_mfma_f32_16x16x16_bf16 v[74:77], v[34:35], v[10:11], 0
	v_mfma_f32_16x16x16_bf16 v[78:81], v[34:35], v[12:13], 0
	s_nop 7
	ds_write2_b32 v91, v74, v78 offset0:64 offset1:80
	ds_write2_b32 v91, v75, v79 offset0:196 offset1:212
	ds_write2_b32 v52, v76, v80 offset0:72 offset1:88
	ds_write2_b32 v52, v77, v81 offset0:204 offset1:220
	s_waitcnt lgkmcnt(12)
	v_mfma_f32_16x16x16_bf16 v[74:77], v[34:35], v[14:15], 0
	v_mfma_f32_16x16x16_bf16 v[34:37], v[34:35], v[16:17], 0
	s_nop 7
	ds_write2_b32 v91, v74, v34 offset0:96 offset1:112
	ds_write2_b32 v91, v75, v35 offset0:228 offset1:244
	ds_write2_b32 v52, v76, v36 offset0:104 offset1:120
	ds_write2_b32 v52, v77, v37 offset0:236 offset1:252
	ds_read2_b64 v[34:37], v92 offset1:66
	v_pk_mul_f32 v[52:53], v[38:39], v[48:49]
	ds_read2_b64 v[74:77], v57 offset0:24 offset1:90
	ds_read2_b64 v[78:81], v57 offset0:156 offset1:222
	v_pk_fma_f32 v[96:97], v[42:43], v[48:49], v[52:53] op_sel:[0,0,1] op_sel_hi:[1,1,0] neg_lo:[0,0,1] neg_hi:[0,0,1]
	v_pk_fma_f32 v[48:49], v[42:43], v[48:49], v[52:53] op_sel:[0,0,1] op_sel_hi:[1,1,0]
	s_nop 0
	v_mov_b32_e32 v97, v49
	s_waitcnt lgkmcnt(2)
	v_pk_add_f32 v[34:35], v[96:97], v[34:35]
	s_nop 0
	v_pk_mul_f32 v[48:49], v[38:39], v[34:35]
	v_cvt_pk_bf16_f32 v57, v34, v35
	v_pk_fma_f32 v[52:53], v[42:43], v[34:35], v[48:49] op_sel:[0,0,1] op_sel_hi:[1,1,0] neg_lo:[0,0,1] neg_hi:[0,0,1]
	v_pk_fma_f32 v[34:35], v[42:43], v[34:35], v[48:49] op_sel:[0,0,1] op_sel_hi:[1,1,0]
	s_nop 0
	v_mov_b32_e32 v53, v35
	v_pk_add_f32 v[48:49], v[36:37], v[52:53]
	v_add_u32_e32 v35, 0x2000, v93
	v_cvt_pk_bf16_f32 v34, v48, v49
	ds_write2_b32 v35, v57, v34 offset0:64 offset1:132
	ds_read2_b64 v[34:37], v92 offset0:132 offset1:198
	v_pk_mul_f32 v[52:53], v[38:39], v[48:49]
	s_nop 0
	v_pk_fma_f32 v[96:97], v[42:43], v[48:49], v[52:53] op_sel:[0,0,1] op_sel_hi:[1,1,0] neg_lo:[0,0,1] neg_hi:[0,0,1]
	v_pk_fma_f32 v[48:49], v[42:43], v[48:49], v[52:53] op_sel:[0,0,1] op_sel_hi:[1,1,0]
	s_nop 0
	v_mov_b32_e32 v97, v49
	s_waitcnt lgkmcnt(0)
	v_pk_add_f32 v[34:35], v[34:35], v[96:97]
	s_nop 0
	v_pk_mul_f32 v[48:49], v[38:39], v[34:35]
	v_cvt_pk_bf16_f32 v57, v34, v35
	v_pk_fma_f32 v[52:53], v[42:43], v[34:35], v[48:49] op_sel:[0,0,1] op_sel_hi:[1,1,0] neg_lo:[0,0,1] neg_hi:[0,0,1]
	v_pk_fma_f32 v[34:35], v[42:43], v[34:35], v[48:49] op_sel:[0,0,1] op_sel_hi:[1,1,0]
	s_nop 0
	v_mov_b32_e32 v53, v35
	v_pk_add_f32 v[48:49], v[36:37], v[52:53]
	v_add_u32_e32 v35, 0x2200, v93
	v_cvt_pk_bf16_f32 v34, v48, v49
	ds_write2_b32 v35, v57, v34 offset0:72 offset1:140
	v_add_u32_e32 v57, 0x800, v92
	ds_read2_b64 v[34:37], v57 offset0:8 offset1:74
	v_pk_mul_f32 v[52:53], v[38:39], v[48:49]
	s_nop 0
	v_pk_fma_f32 v[96:97], v[42:43], v[48:49], v[52:53] op_sel:[0,0,1] op_sel_hi:[1,1,0] neg_lo:[0,0,1] neg_hi:[0,0,1]
	v_pk_fma_f32 v[48:49], v[42:43], v[48:49], v[52:53] op_sel:[0,0,1] op_sel_hi:[1,1,0]
	s_nop 0
	v_mov_b32_e32 v97, v49
	s_waitcnt lgkmcnt(0)
	v_pk_add_f32 v[34:35], v[34:35], v[96:97]
	s_nop 0
	v_pk_mul_f32 v[48:49], v[38:39], v[34:35]
	v_cvt_pk_bf16_f32 v73, v34, v35
	v_pk_fma_f32 v[52:53], v[42:43], v[34:35], v[48:49] op_sel:[0,0,1] op_sel_hi:[1,1,0] neg_lo:[0,0,1] neg_hi:[0,0,1]
	v_pk_fma_f32 v[34:35], v[42:43], v[34:35], v[48:49] op_sel:[0,0,1] op_sel_hi:[1,1,0]
	s_nop 0
	v_mov_b32_e32 v53, v35
	v_pk_add_f32 v[48:49], v[36:37], v[52:53]
	v_add_u32_e32 v35, 0x2400, v93
	v_cvt_pk_bf16_f32 v34, v48, v49
	ds_write2_b32 v35, v73, v34 offset0:80 offset1:148
	ds_read2_b64 v[34:37], v57 offset0:140 offset1:206
	v_pk_mul_f32 v[52:53], v[38:39], v[48:49]
	s_nop 0
	v_pk_fma_f32 v[96:97], v[42:43], v[48:49], v[52:53] op_sel:[0,0,1] op_sel_hi:[1,1,0] neg_lo:[0,0,1] neg_hi:[0,0,1]
	v_pk_fma_f32 v[48:49], v[42:43], v[48:49], v[52:53] op_sel:[0,0,1] op_sel_hi:[1,1,0]
	s_nop 0
	v_mov_b32_e32 v97, v49
	s_waitcnt lgkmcnt(0)
; DI void phase_scan(const Params& p, int j, unsigned char* shm, int wv) {
;     ...
;       for (int t = 0; t < 16; ++t) bv[t] = *(const float2*)(bu + t * 132 + 2 * pst);
; #pragma unroll
;       for (int t = 0; t < 16; ++t) {
;         const float nr = abr * hr - abi * hi + bv[t].x;
;         const float ni = abr * hi + abi * hr + bv[t].y;
;         hr = nr; hi = ni;
;         *(unsigned*)(Hl + t * 136 + 2 * pst) = pack2(hr, hi);
;       }
;       __builtin_amdgcn_wave_barrier();
;       f32x4 y = {0.f, 0.f, 0.f, 0.f};
; #pragma unroll
;       for (int kb = 0; kb < 4; ++kb) {
;         bf16x8 af = *(const bf16x8*)(Hl + col * 136 + kb * 32 + quad * 8);
;         y = __builtin_amdgcn_mfma_f32_16x16x32_bf16(cop[kb], af, y, 0, 0, 0);
;       }
;       {
;         const int tok = ssm_tok(d, b, tau0 + col);
;         uint2 o; o.x = pack2(y[0], y[1]); o.y = pack2(y[2], y[3]);
;         *(uint2*)(Rd + (size_t)tok * 512 + g * 16 + quad * 4) = o;
	v_pk_add_f32 v[34:35], v[34:35], v[96:97]
	s_nop 0
	v_pk_mul_f32 v[48:49], v[38:39], v[34:35]
	v_cvt_pk_bf16_f32 v57, v34, v35
	v_pk_fma_f32 v[52:53], v[42:43], v[34:35], v[48:49] op_sel:[0,0,1] op_sel_hi:[1,1,0] neg_lo:[0,0,1] neg_hi:[0,0,1]
	v_pk_fma_f32 v[34:35], v[42:43], v[34:35], v[48:49] op_sel:[0,0,1] op_sel_hi:[1,1,0]
	s_nop 0
	v_mov_b32_e32 v53, v35
	v_pk_add_f32 v[48:49], v[36:37], v[52:53]
	v_add_u32_e32 v35, 0x2600, v93
	v_cvt_pk_bf16_f32 v34, v48, v49
	ds_write2_b32 v35, v57, v34 offset0:88 offset1:156
	v_add_u32_e32 v57, 0x1000, v92
	ds_read2_b64 v[34:37], v57 offset0:16 offset1:82
	v_pk_mul_f32 v[52:53], v[38:39], v[48:49]
	s_nop 0
	v_pk_fma_f32 v[96:97], v[42:43], v[48:49], v[52:53] op_sel:[0,0,1] op_sel_hi:[1,1,0] neg_lo:[0,0,1] neg_hi:[0,0,1]
	v_pk_fma_f32 v[48:49], v[42:43], v[48:49], v[52:53] op_sel:[0,0,1] op_sel_hi:[1,1,0]
	s_nop 0
	v_mov_b32_e32 v97, v49
	s_waitcnt lgkmcnt(0)
	v_pk_add_f32 v[34:35], v[34:35], v[96:97]
	s_nop 0
	v_pk_mul_f32 v[48:49], v[38:39], v[34:35]
	v_cvt_pk_bf16_f32 v73, v34, v35
	v_pk_fma_f32 v[52:53], v[42:43], v[34:35], v[48:49] op_sel:[0,0,1] op_sel_hi:[1,1,0] neg_lo:[0,0,1] neg_hi:[0,0,1]
	v_pk_fma_f32 v[34:35], v[42:43], v[34:35], v[48:49] op_sel:[0,0,1] op_sel_hi:[1,1,0]
	s_nop 0
	v_mov_b32_e32 v53, v35
	v_pk_add_f32 v[48:49], v[36:37], v[52:53]
	v_add_u32_e32 v35, 0x2800, v93
	v_cvt_pk_bf16_f32 v34, v48, v49
	ds_write2_b32 v35, v73, v34 offset0:96 offset1:164
	ds_read2_b64 v[34:37], v57 offset0:148 offset1:214
	v_pk_mul_f32 v[52:53], v[38:39], v[48:49]
	s_nop 0
	v_pk_fma_f32 v[96:97], v[42:43], v[48:49], v[52:53] op_sel:[0,0,1] op_sel_hi:[1,1,0] neg_lo:[0,0,1] neg_hi:[0,0,1]
	v_pk_fma_f32 v[48:49], v[42:43], v[48:49], v[52:53] op_sel:[0,0,1] op_sel_hi:[1,1,0]
	s_nop 0
	v_mov_b32_e32 v97, v49
	s_waitcnt lgkmcnt(0)
	v_pk_add_f32 v[34:35], v[34:35], v[96:97]
	s_nop 0
	v_pk_mul_f32 v[48:49], v[38:39], v[34:35]
	v_cvt_pk_bf16_f32 v57, v34, v35
	v_pk_fma_f32 v[52:53], v[42:43], v[34:35], v[48:49] op_sel:[0,0,1] op_sel_hi:[1,1,0] neg_lo:[0,0,1] neg_hi:[0,0,1]
	v_pk_fma_f32 v[34:35], v[42:43], v[34:35], v[48:49] op_sel:[0,0,1] op_sel_hi:[1,1,0]
	s_nop 0
	v_mov_b32_e32 v53, v35
	v_pk_add_f32 v[34:35], v[36:37], v[52:53]
	v_add_u32_e32 v37, 0x2a00, v93
	v_cvt_pk_bf16_f32 v36, v34, v35
	ds_write2_b32 v37, v57, v36 offset0:104 offset1:172
	v_pk_mul_f32 v[36:37], v[38:39], v[34:35]
	v_or_b32_e32 v53, s20, v82
	v_pk_fma_f32 v[48:49], v[42:43], v[34:35], v[36:37] op_sel:[0,0,1] op_sel_hi:[1,1,0] neg_lo:[0,0,1] neg_hi:[0,0,1]
	v_pk_fma_f32 v[34:35], v[42:43], v[34:35], v[36:37] op_sel:[0,0,1] op_sel_hi:[1,1,0]
	s_nop 0
	v_mov_b32_e32 v49, v35
	v_pk_add_f32 v[34:35], v[74:75], v[48:49]
	s_nop 0
	v_pk_mul_f32 v[36:37], v[38:39], v[34:35]
	v_cvt_pk_bf16_f32 v52, v34, v35
	v_pk_fma_f32 v[48:49], v[42:43], v[34:35], v[36:37] op_sel:[0,0,1] op_sel_hi:[1,1,0] neg_lo:[0,0,1] neg_hi:[0,0,1]
	v_pk_fma_f32 v[34:35], v[42:43], v[34:35], v[36:37] op_sel:[0,0,1] op_sel_hi:[1,1,0]
	v_add_u32_e32 v37, 0x2c00, v93
	v_mov_b32_e32 v49, v35
	v_pk_add_f32 v[34:35], v[76:77], v[48:49]
	s_nop 0
	v_cvt_pk_bf16_f32 v36, v34, v35
	ds_write2_b32 v37, v52, v36 offset0:112 offset1:180
	v_pk_mul_f32 v[36:37], v[38:39], v[34:35]
	s_nop 0
	v_pk_fma_f32 v[48:49], v[42:43], v[34:35], v[36:37] op_sel:[0,0,1] op_sel_hi:[1,1,0] neg_lo:[0,0,1] neg_hi:[0,0,1]
	v_pk_fma_f32 v[34:35], v[42:43], v[34:35], v[36:37] op_sel:[0,0,1] op_sel_hi:[1,1,0]
	s_nop 0
	v_mov_b32_e32 v49, v35
	v_pk_add_f32 v[34:35], v[78:79], v[48:49]
	s_nop 0
	v_pk_mul_f32 v[36:37], v[38:39], v[34:35]
	v_cvt_pk_bf16_f32 v52, v34, v35
	v_pk_fma_f32 v[48:49], v[42:43], v[34:35], v[36:37] op_sel:[0,0,1] op_sel_hi:[1,1,0] neg_lo:[0,0,1] neg_hi:[0,0,1]
	v_pk_fma_f32 v[34:35], v[42:43], v[34:35], v[36:37] op_sel:[0,0,1] op_sel_hi:[1,1,0]
	s_nop 0
	v_mov_b32_e32 v49, v35
	v_pk_add_f32 v[48:49], v[80:81], v[48:49]
	v_add_u32_e32 v35, 0x2e00, v93
	v_cvt_pk_bf16_f32 v34, v48, v49
	ds_write2_b32 v35, v52, v34 offset0:120 offset1:188
	ds_read_b128 v[34:37], v94 offset:8448
	ds_read_b128 v[74:77], v94 offset:8512
	s_waitcnt lgkmcnt(1)
	v_mfma_f32_16x16x32_bf16 v[34:37], v[18:21], v[34:37], 0
	s_waitcnt lgkmcnt(0)
	v_mfma_f32_16x16x32_bf16 v[34:37], v[22:25], v[74:77], v[34:37]
	ds_read_b128 v[74:77], v94 offset:8576
	s_waitcnt lgkmcnt(0)
	v_mfma_f32_16x16x32_bf16 v[34:37], v[26:29], v[74:77], v[34:37]
	ds_read_b128 v[74:77], v94 offset:8640
	s_waitcnt lgkmcnt(0)
	v_mfma_f32_16x16x32_bf16 v[34:37], v[30:33], v[74:77], v[34:37]
	s_and_saveexec_b64 s[12:13], s[24:25]
	s_xor_b64 s[12:13], exec, s[12:13]
	s_cbranch_execz .LBB0_872
	s_mov_b64 s[14:15], -1
	s_and_b64 vcc, exec, s[8:9]
	s_cbranch_vccz .LBB0_869
	v_sub_u32_e32 v52, v0, v53
	s_mov_b64 s[14:15], 0

; #define PROLOGUE_STAGES(br_, bc_) do { \
;     STAGEB(SB(0, 0), bc_, 0); STAGEA(SA(0, 0), br_, 0); STAGEB(SB(0, 1), (bc_) + HALF, 0); STAGEA(SA(0, 1), (br_) + HALF, 0); \
;     STAGEB(SB(1, 0), bc_, 1); STAGEA(SA(1, 0), br_, 1); STAGEB(SB(1, 1), (bc_) + HALF, 1); } while (0)
; template <int EPI>
; DI void gemm_phase(const u16* __restrict__ A, int lda, const u16* __restrict__ Bt, int ldb,
;                    int M, int N, int K, const Epi& e, unsigned char* shmraw, int wv, int slot) {
;     ...
;   int T = slot, pm = 0, pn = 0, st_;
;   while ((st_ = gemm_decode(T, nsuper, nNs, SWM, SWN, nM, pm, pn)) == 0) T += nb;
;   if (st_ < 0) return;
;     ...
;   PROLOGUE_STAGES(pm * BM, pn * BM);
.LBB0_1036:
	s_movk_i32 vcc_lo, 0x480
	s_add_i32 vcc_hi, s34, -1
	s_and_b32 vcc_lo, vcc_lo, vcc_hi
	s_cmp_eq_u32 vcc_lo, 0
	s_cbranch_scc1 .Lmy_stg_r1004
	s_sub_i32 vcc_hi, s17, s34
	s_cmp_lt_i32 vcc_hi, vcc_lo
	s_cbranch_scc1 .Lmy_stg_r1004
	s_sleep 127
	s_sleep 127
	s_sleep 127

; #define PROLOGUE_STAGES(br_, bc_) do { \
;     STAGEB(SB(0, 0), bc_, 0); STAGEA(SA(0, 0), br_, 0); STAGEB(SB(0, 1), (bc_) + HALF, 0); STAGEA(SA(0, 1), (br_) + HALF, 0); \
;     STAGEB(SB(1, 0), bc_, 1); STAGEA(SA(1, 0), br_, 1); STAGEB(SB(1, 1), (bc_) + HALF, 1); } while (0)
; template <int EPI>
; DI void gemm_phase(const u16* __restrict__ A, int lda, const u16* __restrict__ Bt, int ldb,
;                    int M, int N, int K, const Epi& e, unsigned char* shmraw, int wv, int slot) {
;     ...
;   int T = slot, pm = 0, pn = 0, st_;
;   while ((st_ = gemm_decode(T, nsuper, nNs, SWM, SWN, nM, pm, pn)) == 0) T += nb;
;   if (st_ < 0) return;
;     ...
;   PROLOGUE_STAGES(pm * BM, pn * BM);
.LBB0_1225:
	s_lshl_b32 vcc_lo, s42, 5
	s_add_i32 vcc_hi, s34, -1
	s_and_b32 vcc_lo, vcc_lo, vcc_hi
	s_cmp_eq_u32 vcc_lo, 0
	s_cbranch_scc1 .Lmy_stg_r1172
	s_sub_i32 vcc_hi, s43, s34
	s_cmp_lt_i32 vcc_hi, vcc_lo
	s_cbranch_scc1 .Lmy_stg_r1172
	s_sleep 127
	s_sleep 127
	s_sleep 127
